# baseline (speedup 1.0000x reference)
.LBB0_138:
	s_lshl_b32 s0, s14, 4
	s_and_b32 s1, s0, 0x70
	s_bfe_u32 s8, s14, 0x40005
	s_or_b32 s1, s1, s8
	s_lshl_b32 s9, s1, 7
	s_and_b32 s0, s0, 0x180
	s_and_b32 s1, s14, 0xfffffe00
	s_or_b32 s0, s0, s1
	v_mov_b32_e32 v116, v144
	s_ashr_i32 s1, s0, 31
	v_mov_b32_e32 v42, v144
	s_lshl_b64 s[10:11], s[0:1], 11
	v_ashrrev_i32_e32 v0, 3, v116
	v_add_u32_e32 v2, s9, v0
	v_ashrrev_i32_e32 v34, 3, v42
	s_add_u32 s10, s12, s10
	v_lshlrev_b32_e32 v0, 3, v42
	v_ashrrev_i32_e32 v35, 31, v34
	s_addc_u32 s11, s13, s11
	v_and_b32_e32 v43, 56, v0
	v_lshlrev_b64 v[4:5], 11, v[34:35]
	v_lshl_add_u64 v[4:5], s[10:11], 0, v[4:5]
	v_lshlrev_b32_e32 v0, 1, v43
	v_lshl_add_u64 v[98:99], v[4:5], 0, v[0:1]
	v_add_co_u32_e32 v36, vcc, s33, v98
	v_ashrrev_i32_e32 v3, 31, v2
	s_nop 0
	v_addc_co_u32_e32 v37, vcc, 0, v99, vcc
	v_add_co_u32_e32 v38, vcc, s87, v98
	v_lshlrev_b64 v[2:3], 11, v[2:3]
	s_nop 0
	v_addc_co_u32_e32 v39, vcc, 0, v99, vcc
	s_mov_b32 s1, 0x30000
	v_lshl_add_u64 v[2:3], s[4:5], 0, v[2:3]
	v_add_co_u32_e32 v40, vcc, s1, v98
	v_lshl_add_u64 v[100:101], v[2:3], 0, v[0:1]
	s_nop 0
	v_addc_co_u32_e32 v41, vcc, 0, v99, vcc
	v_add_co_u32_e32 v22, vcc, s33, v100
	s_movk_i32 s10, 0x48
	s_nop 0
	v_addc_co_u32_e32 v23, vcc, 0, v101, vcc
	v_add_co_u32_e32 v26, vcc, s87, v100
	v_mul_lo_u32 v0, v34, s10
	s_nop 0
	v_addc_co_u32_e32 v27, vcc, 0, v101, vcc
	v_add_co_u32_e32 v30, vcc, s1, v100
	s_mov_b64 s[10:11], 0x10000
	s_nop 0
	v_addc_co_u32_e32 v31, vcc, 0, v101, vcc
	s_mov_b64 s[34:35], 0x20000
	s_mov_b64 s[38:39], 0x30000
	global_load_dwordx4 v[2:5], v[98:99], off
	global_load_dwordx4 v[6:9], v[36:37], off
	global_load_dwordx4 v[10:13], v[38:39], off
	global_load_dwordx4 v[14:17], v[40:41], off
	global_load_dwordx4 v[18:21], v[100:101], off
	v_lshl_add_u64 v[108:109], v[100:101], 0, s[10:11]
	global_load_dwordx4 v[22:25], v[22:23], off
	s_nop 0
	global_load_dwordx4 v[26:29], v[26:27], off
	s_nop 0
	global_load_dwordx4 v[30:33], v[30:31], off
	v_lshl_add_u64 v[110:111], v[100:101], 0, s[34:35]
	v_lshl_add_u64 v[112:113], v[100:101], 0, s[38:39]
	global_load_dwordx4 v[78:81], v[98:99], off offset:128
	global_load_dwordx4 v[66:69], v[100:101], off offset:128
	global_load_dwordx4 v[86:89], v[36:37], off offset:128
	global_load_dwordx4 v[70:73], v[38:39], off offset:128
	global_load_dwordx4 v[74:77], v[40:41], off offset:128
	global_load_dwordx4 v[82:85], v[108:109], off offset:128
	global_load_dwordx4 v[90:93], v[110:111], off offset:128
	global_load_dwordx4 v[94:97], v[112:113], off offset:128
	v_readfirstlane_b32 s1, v42
	v_add_lshl_u32 v0, v0, v43, 1
	v_lshl_add_u64 v[102:103], v[98:99], 0, s[10:11]
	s_lshr_b32 s10, s1, 1
	v_and_b32_e32 v35, 31, v42
	s_and_b32 s10, s10, 0xfffffc0
	s_mov_b32 s8, 0
	v_lshl_add_u64 v[104:105], v[98:99], 0, s[34:35]
	v_lshl_add_u64 v[106:107], v[98:99], 0, s[38:39]
	v_add_u32_e32 v117, 0xd800, v0
	s_waitcnt vmcnt(15)
	ds_write_b128 v0, v[2:5]
	s_waitcnt vmcnt(11)
	ds_write_b128 v0, v[18:21] offset:36864
	ds_write_b128 v0, v[6:9] offset:4608
	ds_write_b128 v0, v[10:13] offset:9216
	ds_write_b128 v0, v[14:17] offset:13824
	s_waitcnt vmcnt(10)
	ds_write_b128 v0, v[22:25] offset:41472
	s_waitcnt vmcnt(9)
	ds_write_b128 v0, v[26:29] offset:46080
	s_waitcnt vmcnt(8)
	ds_write_b128 v0, v[30:33] offset:50688
	v_lshrrev_b32_e32 v2, 1, v42
	v_or_b32_e32 v3, s10, v35
	v_and_b32_e32 v2, 16, v2
	s_movk_i32 s10, 0x90
	v_mad_u64_u32 v[114:115], s[10:11], v3, s10, v[2:3]
	v_and_or_b32 v3, s1, 64, v35
	v_mul_u32_u24_e32 v3, 0x48, v3
	v_lshl_add_u32 v115, v3, 1, v2
	v_mov_b32_e32 v2, 0
	s_movk_i32 s1, 0xc0
	v_mov_b32_e32 v3, v2
	v_mov_b32_e32 v4, v2
	v_mov_b32_e32 v5, v2
	v_mov_b32_e32 v6, v2
	v_mov_b32_e32 v7, v2
	v_mov_b32_e32 v8, v2
	v_mov_b32_e32 v9, v2
	v_mov_b32_e32 v10, v2
	v_mov_b32_e32 v11, v2
	v_mov_b32_e32 v12, v2
	v_mov_b32_e32 v13, v2
	v_mov_b32_e32 v14, v2
	v_mov_b32_e32 v15, v2
	v_mov_b32_e32 v16, v2
	v_mov_b32_e32 v17, v2
	v_mov_b32_e32 v18, v2
	v_mov_b32_e32 v19, v2
	v_mov_b32_e32 v20, v2
	v_mov_b32_e32 v21, v2
	v_mov_b32_e32 v22, v2
	v_mov_b32_e32 v23, v2
	v_mov_b32_e32 v24, v2
	v_mov_b32_e32 v25, v2
	v_mov_b32_e32 v26, v2
	v_mov_b32_e32 v27, v2
	v_mov_b32_e32 v28, v2
	v_mov_b32_e32 v29, v2
	v_mov_b32_e32 v30, v2
	v_mov_b32_e32 v31, v2
	v_mov_b32_e32 v32, v2
	v_mov_b32_e32 v33, v2
	v_mov_b32_e32 v34, v2
	v_mov_b32_e32 v35, v2
	v_mov_b32_e32 v36, v2
	v_mov_b32_e32 v37, v2
	v_mov_b32_e32 v38, v2
	v_mov_b32_e32 v39, v2
	v_mov_b32_e32 v40, v2
	v_mov_b32_e32 v41, v2
	v_mov_b32_e32 v42, v2
	v_mov_b32_e32 v43, v2
	v_mov_b32_e32 v44, v2
	v_mov_b32_e32 v45, v2
	v_mov_b32_e32 v46, v2
	v_mov_b32_e32 v47, v2
	v_mov_b32_e32 v48, v2
	v_mov_b32_e32 v49, v2
	v_mov_b32_e32 v50, v2
	v_mov_b32_e32 v51, v2
	v_mov_b32_e32 v52, v2
	v_mov_b32_e32 v53, v2
	v_mov_b32_e32 v54, v2
	v_mov_b32_e32 v55, v2
	v_mov_b32_e32 v56, v2
	v_mov_b32_e32 v57, v2
	v_mov_b32_e32 v58, v2
	v_mov_b32_e32 v59, v2
	v_mov_b32_e32 v60, v2
	v_mov_b32_e32 v61, v2
	v_mov_b32_e32 v62, v2
	v_mov_b32_e32 v63, v2
	v_mov_b32_e32 v64, v2
	v_mov_b32_e32 v65, v2
	s_waitcnt lgkmcnt(0)
	s_barrier
	s_nop 0
	s_nop 0
	s_nop 0
	s_nop 0
	s_nop 0
	s_nop 0
.LBB0_139:
	s_waitcnt vmcnt(7)
	ds_write_b128 v0, v[78:81] offset:18432
	s_waitcnt vmcnt(5)
	ds_write_b128 v0, v[86:89] offset:23040
	s_add_i32 s10, s8, 2
	s_sub_i32 s11, s1, 64
	ds_read_b128 v[78:81], v114
	ds_read_b128 v[86:89], v115 offset:36864
	ds_read_b128 v[118:121], v114 offset:4608
	ds_read_b128 v[122:125], v115 offset:41472
	s_cmp_lt_u32 s8, 14
	s_cselect_b64 s[34:35], -1, 0
	s_and_b64 vcc, s[34:35], exec
	s_cselect_b32 s16, s11, 0
	s_lshl_b64 s[34:35], s[16:17], 1
	s_waitcnt lgkmcnt(2)
	v_mfma_f32_32x32x16_bf16 v[50:65], v[78:81], v[86:89], v[50:65]
	v_lshl_add_u64 v[126:127], v[102:103], 0, s[34:35]
	s_waitcnt lgkmcnt(0)
	v_mfma_f32_32x32x16_bf16 v[34:49], v[78:81], v[122:125], v[34:49]
	v_lshl_add_u64 v[78:79], v[98:99], 0, s[34:35]
	v_mfma_f32_32x32x16_bf16 v[18:33], v[118:121], v[86:89], v[18:33]
	global_load_dwordx4 v[78:81], v[78:79], off
	s_nop 0
	global_load_dwordx4 v[86:89], v[126:127], off
	v_mfma_f32_32x32x16_bf16 v[2:17], v[118:121], v[122:125], v[2:17]
	s_waitcnt vmcnt(6)
	ds_write_b128 v0, v[70:73] offset:27648
	s_waitcnt vmcnt(5)
	ds_write_b128 v0, v[74:77] offset:32256
	ds_read_b128 v[70:73], v114 offset:32
	ds_read_b128 v[74:77], v115 offset:36896
	ds_read_b128 v[118:121], v114 offset:4640
	ds_read_b128 v[122:125], v115 offset:41504
	v_lshl_add_u64 v[126:127], v[106:107], 0, s[34:35]
	s_waitcnt lgkmcnt(2)
	v_mfma_f32_32x32x16_bf16 v[50:65], v[70:73], v[74:77], v[50:65]
	s_waitcnt lgkmcnt(0)
	v_mfma_f32_32x32x16_bf16 v[34:49], v[70:73], v[122:125], v[34:49]
	v_lshl_add_u64 v[70:71], v[104:105], 0, s[34:35]
	v_mfma_f32_32x32x16_bf16 v[18:33], v[118:121], v[74:77], v[18:33]
	global_load_dwordx4 v[70:73], v[70:71], off
	s_nop 0
	global_load_dwordx4 v[74:77], v[126:127], off
	v_mfma_f32_32x32x16_bf16 v[2:17], v[118:121], v[122:125], v[2:17]
	ds_write_b128 v0, v[66:69] offset:55296
	s_waitcnt vmcnt(6)
	ds_write_b128 v0, v[82:85] offset:59904
	ds_read_b128 v[66:69], v114 offset:64
	ds_read_b128 v[82:85], v115 offset:36928
	ds_read_b128 v[118:121], v114 offset:4672
	ds_read_b128 v[122:125], v115 offset:41536
	v_lshl_add_u64 v[126:127], v[108:109], 0, s[34:35]
	s_waitcnt lgkmcnt(2)
	v_mfma_f32_32x32x16_bf16 v[50:65], v[66:69], v[82:85], v[50:65]
	s_waitcnt lgkmcnt(0)
	v_mfma_f32_32x32x16_bf16 v[34:49], v[66:69], v[122:125], v[34:49]
	v_lshl_add_u64 v[66:67], v[100:101], 0, s[34:35]
	v_mfma_f32_32x32x16_bf16 v[18:33], v[118:121], v[82:85], v[18:33]
	global_load_dwordx4 v[66:69], v[66:67], off
	s_nop 0
	global_load_dwordx4 v[82:85], v[126:127], off
	v_mfma_f32_32x32x16_bf16 v[2:17], v[118:121], v[122:125], v[2:17]
	s_waitcnt vmcnt(7)
	ds_write_b128 v0, v[90:93] offset:64512
	s_waitcnt vmcnt(6)
	ds_write_b128 v117, v[94:97] offset:13824
	ds_read_b128 v[90:93], v114 offset:96
	ds_read_b128 v[94:97], v115 offset:36960
	ds_read_b128 v[118:121], v114 offset:4704
	ds_read_b128 v[122:125], v115 offset:41568
	v_lshl_add_u64 v[126:127], v[112:113], 0, s[34:35]
	s_waitcnt lgkmcnt(2)
	v_mfma_f32_32x32x16_bf16 v[50:65], v[90:93], v[94:97], v[50:65]
	s_waitcnt lgkmcnt(0)
	v_mfma_f32_32x32x16_bf16 v[34:49], v[90:93], v[122:125], v[34:49]
	v_lshl_add_u64 v[90:91], v[110:111], 0, s[34:35]
	v_mfma_f32_32x32x16_bf16 v[18:33], v[118:121], v[94:97], v[18:33]
	global_load_dwordx4 v[90:93], v[90:91], off
	s_nop 0
	global_load_dwordx4 v[94:97], v[126:127], off
	v_mfma_f32_32x32x16_bf16 v[2:17], v[118:121], v[122:125], v[2:17]
	s_barrier
	s_waitcnt vmcnt(7)
	ds_write_b128 v0, v[78:81]
	s_waitcnt vmcnt(6)
	ds_write_b128 v0, v[86:89] offset:4608
	ds_read_b128 v[78:81], v114 offset:18432
	ds_read_b128 v[86:89], v115 offset:55296
	ds_read_b128 v[118:121], v114 offset:23040
	ds_read_b128 v[122:125], v115 offset:59904
	s_cmp_lt_u32 s8, 13
	s_cselect_b32 s16, s1, 0
	s_lshl_b64 s[34:35], s[16:17], 1
	s_waitcnt lgkmcnt(2)
	v_mfma_f32_32x32x16_bf16 v[50:65], v[78:81], v[86:89], v[50:65]
	v_lshl_add_u64 v[126:127], v[102:103], 0, s[34:35]
	s_waitcnt lgkmcnt(0)
	v_mfma_f32_32x32x16_bf16 v[34:49], v[78:81], v[122:125], v[34:49]
	v_lshl_add_u64 v[78:79], v[98:99], 0, s[34:35]
	v_mfma_f32_32x32x16_bf16 v[18:33], v[118:121], v[86:89], v[18:33]
	global_load_dwordx4 v[78:81], v[78:79], off
	s_nop 0
	global_load_dwordx4 v[86:89], v[126:127], off
	v_mfma_f32_32x32x16_bf16 v[2:17], v[118:121], v[122:125], v[2:17]
	s_waitcnt vmcnt(7)
	ds_write_b128 v0, v[70:73] offset:9216
	s_waitcnt vmcnt(6)
	ds_write_b128 v0, v[74:77] offset:13824
	ds_read_b128 v[70:73], v114 offset:18464
	ds_read_b128 v[74:77], v115 offset:55328
	ds_read_b128 v[118:121], v114 offset:23072
	ds_read_b128 v[122:125], v115 offset:59936
	v_lshl_add_u64 v[126:127], v[106:107], 0, s[34:35]
	s_waitcnt lgkmcnt(2)
	v_mfma_f32_32x32x16_bf16 v[50:65], v[70:73], v[74:77], v[50:65]
	s_waitcnt lgkmcnt(0)
	v_mfma_f32_32x32x16_bf16 v[34:49], v[70:73], v[122:125], v[34:49]
	v_lshl_add_u64 v[70:71], v[104:105], 0, s[34:35]
	v_mfma_f32_32x32x16_bf16 v[18:33], v[118:121], v[74:77], v[18:33]
	global_load_dwordx4 v[70:73], v[70:71], off
	s_nop 0
	global_load_dwordx4 v[74:77], v[126:127], off
	v_mfma_f32_32x32x16_bf16 v[2:17], v[118:121], v[122:125], v[2:17]
	s_waitcnt vmcnt(7)
	ds_write_b128 v0, v[66:69] offset:36864
	s_waitcnt vmcnt(6)
	ds_write_b128 v0, v[82:85] offset:41472
	ds_read_b128 v[66:69], v114 offset:18496
	ds_read_b128 v[82:85], v115 offset:55360
	ds_read_b128 v[118:121], v114 offset:23104
	ds_read_b128 v[122:125], v115 offset:59968
	v_lshl_add_u64 v[126:127], v[108:109], 0, s[34:35]
	s_waitcnt lgkmcnt(2)
	v_mfma_f32_32x32x16_bf16 v[50:65], v[66:69], v[82:85], v[50:65]
	s_waitcnt lgkmcnt(0)
	v_mfma_f32_32x32x16_bf16 v[34:49], v[66:69], v[122:125], v[34:49]
	v_lshl_add_u64 v[66:67], v[100:101], 0, s[34:35]
	v_mfma_f32_32x32x16_bf16 v[18:33], v[118:121], v[82:85], v[18:33]
	global_load_dwordx4 v[66:69], v[66:67], off
	s_nop 0
	global_load_dwordx4 v[82:85], v[126:127], off
	v_mfma_f32_32x32x16_bf16 v[2:17], v[118:121], v[122:125], v[2:17]
	s_waitcnt vmcnt(7)
	ds_write_b128 v0, v[90:93] offset:46080
	s_waitcnt vmcnt(6)
	ds_write_b128 v0, v[94:97] offset:50688
	ds_read_b128 v[90:93], v114 offset:18528
	ds_read_b128 v[94:97], v115 offset:55392
	ds_read_b128 v[118:121], v114 offset:23136
	ds_read_b128 v[122:125], v115 offset:60000
	v_lshl_add_u64 v[126:127], v[112:113], 0, s[34:35]
	s_waitcnt lgkmcnt(2)
	v_mfma_f32_32x32x16_bf16 v[50:65], v[90:93], v[94:97], v[50:65]
	s_waitcnt lgkmcnt(0)
	v_mfma_f32_32x32x16_bf16 v[34:49], v[90:93], v[122:125], v[34:49]
	v_lshl_add_u64 v[90:91], v[110:111], 0, s[34:35]
	v_mfma_f32_32x32x16_bf16 v[18:33], v[118:121], v[94:97], v[18:33]
	global_load_dwordx4 v[90:93], v[90:91], off
	s_nop 0
	global_load_dwordx4 v[94:97], v[126:127], off
	v_mfma_f32_32x32x16_bf16 v[2:17], v[118:121], v[122:125], v[2:17]
	s_addk_i32 s1, 0x80
	s_mov_b32 s8, s10
	s_barrier
	s_cbranch_vccnz .LBB0_139
	s_nop 0
	s_nop 0
	s_nop 0
	s_nop 0
	s_nop 0
	s_nop 0
	s_nop 0
	s_nop 0
	s_nop 0
	s_nop 0
	v_readfirstlane_b32 s1, v116
	s_and_b32 s10, s1, 64
	s_ashr_i32 s1, s1, 1
	v_lshrrev_b32_e32 v0, 3, v116
	s_andn2_b32 s1, s1, 63
	s_waitcnt vmcnt(3)
	v_and_b32_e32 v66, 4, v0
	v_and_or_b32 v0, v116, 31, s10
	s_add_i32 s8, s1, s0
	v_or_b32_e32 v76, s9, v0
	v_lshlrev_b32_e32 v0, 5, v76
	v_or_b32_e32 v72, s8, v66
	v_lshl_add_u64 v[68:69], s[24:25], 0, v[0:1]
	v_cmp_lt_i32_e32 vcc, s46, v72
	s_and_saveexec_b64 s[0:1], vcc
	s_xor_b64 s[0:1], exec, s[0:1]
	s_cbranch_execz .LBB0_143
	s_cmpk_gt_u32 s8, 0x9a7
	s_cbranch_scc1 .LBB0_143
	v_add_u32_e32 v0, 0xfffff660, v72
	v_lshlrev_b64 v[70:71], 2, v[0:1]
	v_lshl_add_u64 v[74:75], s[6:7], 0, v[70:71]
	global_load_dwordx4 v[78:81], v[74:75], off
	v_lshl_add_u64 v[70:71], v[68:69], 0, v[70:71]
	s_waitcnt vmcnt(0)
	v_pk_add_f32 v[78:79], v[50:51], v[78:79]
	v_pk_add_f32 v[80:81], v[52:53], v[80:81]
	global_store_dwordx4 v[70:71], v[78:81], off

.LBB0_482:
	s_add_i32 s40, s40, 2
	s_addk_i32 s41, 0x80
	s_cmp_lt_i32 s44, s15
	s_waitcnt vmcnt(9)
	ds_write_b128 v186, v[2:5] offset:13312
	s_waitcnt vmcnt(8)
	ds_write_b128 v187, v[6:9] offset:13312
	s_waitcnt vmcnt(7)
	ds_write_b128 v188, v[10:13] offset:13312
	s_waitcnt vmcnt(6)
	ds_write_b128 v158, v[136:139] offset:26624
	s_waitcnt vmcnt(5)
	ds_write_b128 v158, v[140:143] offset:32768
	s_waitcnt lgkmcnt(0)
	s_barrier
	s_cbranch_scc0 .LBB0_389
	s_nop 0
	s_nop 0
